# mixer-D early-exit flags via DS ops instead of flat
# speedup vs baseline: 1.0873x; 1.0003x over previous
.LBB0_499:
	s_lshl_b32 s0, s3, 2
	s_and_b32 s0, s0, 16
	s_add_i32 s12, s0, 0x11490
	v_mov_b32_e32 v0, s12
	s_waitcnt lgkmcnt(0)
	s_barrier
	ds_read_b32 v2, v0
	ds_read_b32 v3, v0 offset:4
	ds_read_b32 v4, v0 offset:8
	ds_read_b32 v0, v0 offset:12
	s_add_i32 s3, s3, 4
	s_sub_i32 s82, s82, 64
	v_add_u32_e32 v214, 64, v214
	s_waitcnt lgkmcnt(0)
	v_and_b32_e32 v1, v3, v2
	v_bitop3_b32 v0, v1, v0, v4 bitop3:0x80
	v_cmp_ne_u32_e64 s[0:1], 0, v0
	s_and_b64 s[0:1], exec, s[0:1]
	s_or_b64 s[10:11], s[0:1], s[10:11]
	s_andn2_b64 exec, exec, s[10:11]
	s_cbranch_execz .LBB0_512

.LBB0_506:
	v_cmp_gt_i32_e32 vcc, 0, v213
	s_cbranch_vccnz .LBB0_511
	s_mov_b32 s0, 0xc3480000
	v_cmp_gt_f32_e32 vcc, s0, v141
	s_and_saveexec_b64 s[0:1], s[18:19]
	s_cbranch_execz .LBB0_509
	s_and_b32 s12, s3, 4
	s_cmp_eq_u64 vcc, -1
	v_lshl_add_u32 v0, s12, 2, v208
	s_cselect_b64 s[12:13], -1, 0
	v_cndmask_b32_e64 v2, 0, 1, s[12:13]
	ds_write_b32 v0, v2
